# counted vmcnt waits replaced by full drains placed before the stores (final norm) / at tile prologue; same structure otherwise
# speedup vs baseline: 1.0505x; 1.0040x over previous
; __device__ __forceinline__ void run_phase(int ph, KParams kp, unsigned char* smem) {
;     ...
;       for (int row = wv; row < NTOK; row += nwv) {
;         float* xr = kp->out + (size_t)row * 1024;
;         f32x4 v[4]; float s = 0.f;
; #pragma unroll
;         for (int i = 0; i < 4; ++i) { v[i] = ld_agent_f32x4(xr + i * 256 + lane * 4); s += v[i][0] * v[i][0] + v[i][1] * v[i][1] + v[i][2] * v[i][2] + v[i][3] * v[i][3]; }
;         s += __shfl_xor(s, 1); s += __shfl_xor(s, 2); s += __shfl_xor(s, 4); s += __shfl_xor(s, 8); s += __shfl_xor(s, 16); s += __shfl_xor(s, 32);
;         const float r = rsqrtf(s * (1.0f / 1024.0f) + EPS);
; #pragma unroll
;         for (int i = 0; i < 4; ++i) { const f32x4 g = *(const f32x4*)(kp->g_final + i * 256 + lane * 4); *(f32x4*)(xr + i * 256 + lane * 4) = v[i] * r * g; }
;       }
.Lfn_compute:
	v_mul_f32_e32 v34, v17, v17
	v_fmac_f32_e32 v34, v16, v16
	v_mul_f32_e32 v35, v21, v21
	v_fmac_f32_e32 v35, v20, v20
	v_mul_f32_e32 v36, v25, v25
	v_fmac_f32_e32 v36, v24, v24
	v_pk_mul_f32 v[32:33], v[28:29], v[28:29]
	v_fmac_f32_e32 v34, v18, v18
	v_fmac_f32_e32 v35, v22, v22
	v_add_f32_e32 v32, v32, v33
	v_fmac_f32_e32 v36, v26, v26
	v_fmac_f32_e32 v34, v19, v19
	v_fmac_f32_e32 v35, v23, v23
	v_fmac_f32_e32 v32, v30, v30
	v_fmac_f32_e32 v36, v27, v27
	v_add_f32_e32 v33, v34, v35
	v_fmac_f32_e32 v32, v31, v31
	v_add_f32_e32 v33, v33, v36
	v_add_f32_e32 v32, v33, v32
	ds_bpermute_b32 v33, v6, v32
	s_waitcnt lgkmcnt(0)
	v_add_f32_e32 v32, v32, v33
	ds_bpermute_b32 v33, v7, v32
	s_waitcnt lgkmcnt(0)
	v_add_f32_e32 v32, v32, v33
	ds_bpermute_b32 v33, v8, v32
	s_waitcnt lgkmcnt(0)
	v_add_f32_e32 v32, v32, v33
	ds_bpermute_b32 v33, v9, v32
	s_waitcnt lgkmcnt(0)
	v_add_f32_e32 v32, v32, v33
	ds_bpermute_b32 v33, v10, v32
	s_waitcnt lgkmcnt(0)
	v_add_f32_e32 v32, v32, v33
	ds_bpermute_b32 v33, v11, v32
	s_waitcnt lgkmcnt(0)
	v_add_f32_e32 v32, v32, v33
	v_fmamk_f32 v32, v32, 0x3a800000, v1
	v_mul_f32_e32 v33, 0x4b800000, v32
	v_cmp_gt_f32_e32 vcc, s1, v32
	s_nop 1
	v_cndmask_b32_e32 v32, v32, v33, vcc
	v_rsq_f32_e32 v32, v32
	s_nop 0
	v_mul_f32_e32 v33, 0x45800000, v32
	v_cndmask_b32_e32 v32, v32, v33, vcc
	v_pk_mul_f32 v[16:17], v[16:17], v[32:33] op_sel_hi:[1,0]
	v_pk_mul_f32 v[18:19], v[18:19], v[32:33] op_sel_hi:[1,0]
	v_pk_mul_f32 v[20:21], v[20:21], v[32:33] op_sel_hi:[1,0]
	v_pk_mul_f32 v[22:23], v[22:23], v[32:33] op_sel_hi:[1,0]
	v_pk_mul_f32 v[24:25], v[24:25], v[32:33] op_sel_hi:[1,0]
	v_pk_mul_f32 v[26:27], v[26:27], v[32:33] op_sel_hi:[1,0]
	v_pk_mul_f32 v[28:29], v[28:29], v[32:33] op_sel_hi:[1,0]
	v_pk_mul_f32 v[30:31], v[30:31], v[32:33] op_sel_hi:[1,0]
	v_pk_mul_f32 v[16:17], v[40:41], v[16:17]
	v_pk_mul_f32 v[18:19], v[42:43], v[18:19]
	v_pk_mul_f32 v[20:21], v[44:45], v[20:21]
	v_pk_mul_f32 v[22:23], v[46:47], v[22:23]
	v_pk_mul_f32 v[24:25], v[48:49], v[24:25]
	v_pk_mul_f32 v[26:27], v[50:51], v[26:27]
	v_pk_mul_f32 v[28:29], v[52:53], v[28:29]
	v_pk_mul_f32 v[30:31], v[54:55], v[30:31]
	s_waitcnt vmcnt(0)
	global_store_dwordx4 v[4:5], v[16:19], off
	global_store_dwordx4 v[4:5], v[20:23], off offset:1024
	global_store_dwordx4 v[4:5], v[24:27], off offset:2048
	global_store_dwordx4 v[4:5], v[28:31], off offset:3072
	s_cmp_eq_u32 s13, 0
	s_cbranch_scc1 .LBB0_738
	s_nop 1
	v_mov_b32_e32 v16, v60
	v_mov_b32_e32 v17, v61
	v_mov_b32_e32 v18, v62
	v_mov_b32_e32 v19, v63
	v_mov_b32_e32 v20, v64
	v_mov_b32_e32 v21, v65
	v_mov_b32_e32 v22, v66
	v_mov_b32_e32 v23, v67
	v_mov_b32_e32 v24, v68
	v_mov_b32_e32 v25, v69
	v_mov_b32_e32 v26, v70
	v_mov_b32_e32 v27, v71
	v_mov_b32_e32 v28, v72
	v_mov_b32_e32 v29, v73
	v_mov_b32_e32 v30, v74
	v_mov_b32_e32 v31, v75
	v_mov_b32_e32 v4, v58
	v_mov_b32_e32 v5, v59
	s_branch .Lfn_loop
